# P3: second 32-row half of the LDS layer-norm tile skewed by 32 B (transposing ds_write_b16 2-way instead of 4-way bank conflicts)
# baseline (speedup 1.0000x reference)
; #define LAS __attribute__((address_space(3)))
; #define tid (otid())
; #define wave (__builtin_amdgcn_readfirstlane((int)(threadIdx.x >> 6)))
; __global__ void __launch_bounds__(512, 2) mega_fwd(Args a) {
;     ...
;         constexpr int VLP = 136;
;         LAS bf16_t* VLT = (LAS bf16_t*)lds;
;         const int r32 = lane & 31, hi = lane >> 5, iblk = wave >> 1, dblk = wave & 1;
;         const int jt = tid >> 2, qd = tid & 3;
;         u32x4 r0, r1; f32x4 lgv[4], lbv[4];
;         const int ustep = (G == 256) ? 1 : G;
;         const int jx = vcu & 31;
;         const int u0 = (G == 256) ? (256 * (vcu >> 5) + (jx < 16 ? 7 * jx : 112 + 9 * (jx - 16))) : vcu;
;         const int ucnt = (G == 256) ? (bx < 128 ? 7 : 9) : (vcu < 2048 ? (2047 - vcu) / G + 1 : 0);
;         if (ucnt > 0) { const bf16_t* vp = Z + ((size_t)(u0 >> 3) * 128 + jt) * NZ + 1024 + (u0 & 7) * 64 + 16 * qd; r0 = *(const u32x4*)vp; r1 = *(const u32x4*)(vp + 8);
; #pragma unroll
;             for (int e4 = 0; e4 < 4; ++e4) { lgv[e4] = *(const f32x4*)(KA->gm_ln_g + (u0 & 7) * 64 + 16 * qd + 4 * e4); lbv[e4] = *(const f32x4*)(KA->gm_ln_b + (u0 & 7) * 64 + 16 * qd + 4 * e4); } }
;     ...
;             const float bsp = KA->b_spatial[h * 128 + itok];
;             bf16x8 wf[8];
;             { const bf16_t* wp = WSP + ((size_t)h * 128 + itok) * 128 + 8 * hi;
; #pragma unroll
;               for (int s = 0; s < 8; ++s) if (s < 4 || iblk >= 2) wf[s] = *(const bf16x8*)(wp + 16 * s); }
.Lp3r_entry:
	s_and_b32 s10, s54, 31
	s_and_b32 s22, s10, 7
	s_lshr_b32 s11, s10, 3
	s_mul_i32 s12, s11, 7
	s_mul_i32 s13, s11, 9
	s_sub_u32 s13, s13, 4
	s_cmp_lt_u32 s11, 2
	s_cselect_b32 s12, s12, s13
	s_cselect_b32 s18, 7, 9
	s_and_b32 s39, s39, 0xffffff00
	s_lshr_b32 s39, s39, 3
	s_add_u32 s21, s39, s12
	s_mul_i32 s24, s21, 0x60000
	s_lshl_b32 s25, s22, 7
	s_add_u32 s24, s24, s25
	s_add_u32 s24, s24, 0x6000000
	s_add_u32 s26, s8, s24
	s_addc_u32 s27, s9, 0
	s_lshl_b32 s24, s21, 18
	s_add_u32 s24, s24, s25
	s_add_u32 s24, s24, 0x14a00000
	s_add_u32 s48, s8, s24
	s_addc_u32 s49, s9, 0
	s_lshl_b32 s24, s22, 15
	s_add_u32 s24, s24, 0x180000
	s_add_u32 s36, s8, s24
	s_addc_u32 s37, s9, 0
	s_lshl_b32 s24, s22, 9
	s_add_u32 s46, s16, s24
	s_addc_u32 s47, s17, 0
	s_lshl_b32 s24, s22, 8
	s_add_u32 s50, s40, s24
	s_addc_u32 s51, s41, 0
	s_add_u32 s52, s42, s24
	s_addc_u32 s53, s43, 0
	v_lshlrev_b32_e32 v109, 6, v104
	v_lshrrev_b32_e32 v110, 1, v104
	v_lshl_add_u32 v117, v110, 5, v117
	s_lshl_b32 s23, s5, 5
	v_add_u32_e32 v118, s23, v118
	v_mul_u32_u24_e32 v110, 24, v107
	v_add_u32_e32 v233, v113, v110
	v_add_u32_e32 v234, v116, v110
	global_load_dwordx4 v[120:123], v114, s[36:37]
	global_load_dwordx4 v[124:127], v114, s[36:37] offset:32
	global_load_dwordx4 v[128:131], v114, s[36:37] offset:64
	global_load_dwordx4 v[132:135], v114, s[36:37] offset:96
	global_load_dwordx4 v[136:139], v114, s[36:37] offset:128
	global_load_dwordx4 v[140:143], v114, s[36:37] offset:160
	global_load_dwordx4 v[144:147], v114, s[36:37] offset:192
	global_load_dwordx4 v[148:151], v114, s[36:37] offset:224
	global_load_dword v32, v115, s[46:47]
	global_load_dwordx4 v[152:155], v109, s[50:51]
	global_load_dwordx4 v[156:159], v109, s[50:51] offset:16
	global_load_dwordx4 v[160:163], v109, s[50:51] offset:32
	global_load_dwordx4 v[164:167], v109, s[50:51] offset:48
	global_load_dwordx4 v[168:171], v109, s[52:53]
	global_load_dwordx4 v[172:175], v109, s[52:53] offset:16
	global_load_dwordx4 v[176:179], v109, s[52:53] offset:32
	global_load_dwordx4 v[180:183], v109, s[52:53] offset:48
	s_mov_b32 s45, 0
	global_load_dwordx4 v[16:19], v112, s[26:27]
	global_load_dwordx4 v[20:23], v112, s[26:27] offset:16
	global_load_dwordx4 v[24:27], v233, s[26:27]
	global_load_dwordx4 v[28:31], v233, s[26:27] offset:16
	s_add_u32 s26, s26, 0x60000
	s_addc_u32 s27, s27, 0
	s_cmp_lt_u32 s18, 2
	s_cbranch_scc1 .Lp3r_tail0
	global_load_dwordx4 v[40:43], v112, s[26:27]
	global_load_dwordx4 v[44:47], v112, s[26:27] offset:16
	global_load_dwordx4 v[48:51], v233, s[26:27]
	global_load_dwordx4 v[52:55], v233, s[26:27] offset:16
	s_add_u32 s26, s26, 0x60000
	s_addc_u32 s27, s27, 0

; #define LAS __attribute__((address_space(3)))
; __device__ __forceinline__ unsigned pk2(float lo, float hi) { f32x2_t v = {lo, hi}; bf16x2_t b = __builtin_convertvector(v, bf16x2_t); return __builtin_bit_cast(unsigned, b); }
; __device__ __forceinline__ float bf_lo(unsigned u) { return __uint_as_float(u << 16); }
; __device__ __forceinline__ float bf_hi(unsigned u) { return __uint_as_float(u & 0xffff0000u); }
; __global__ void __launch_bounds__(512, 2) mega_fwd(Args a) {
;     ...
;             {
;                 float xv[16];
;                 xv[0] = bf_lo(r0.x); xv[1] = bf_hi(r0.x); xv[2] = bf_lo(r0.y); xv[3] = bf_hi(r0.y); xv[4] = bf_lo(r0.z); xv[5] = bf_hi(r0.z); xv[6] = bf_lo(r0.w); xv[7] = bf_hi(r0.w);
;                 xv[8] = bf_lo(r1.x); xv[9] = bf_hi(r1.x); xv[10] = bf_lo(r1.y); xv[11] = bf_hi(r1.y); xv[12] = bf_lo(r1.z); xv[13] = bf_hi(r1.z); xv[14] = bf_lo(r1.w); xv[15] = bf_hi(r1.w);
;                 float sm = 0.f;
; #pragma unroll
;                 for (int e = 0; e < 16; ++e) sm += xv[e];
;                 sm += __shfl_xor(sm, 1); sm += __shfl_xor(sm, 2);
;                 const float mu = sm * (1.0f / 64.0f); float q = 0.f;
; #pragma unroll
;                 for (int e = 0; e < 16; ++e) { xv[e] -= mu; q += xv[e] * xv[e]; }
;                 q += __shfl_xor(q, 1); q += __shfl_xor(q, 2);
;                 const float rstd = rsqrtf(q * (1.0f / 64.0f) + EPS);
; #pragma unroll
;                 for (int e = 0; e < 16; ++e) { const float y = xv[e] * rstd * lgv[e >> 2][e & 3] + lbv[e >> 2][e & 3]; VLT[(16 * qd + e) * VLP + jt] = (bf16_t)(pk2(y, 0.f) & 0xffffu); }
;             }
;     ...
;             __syncthreads();
;             {
;                 f32x16 acc;
; #pragma unroll
;                 for (int r = 0; r < 16; ++r) acc[r] = 0.f;
;                 const LAS bf16_t* vl = VLT + (32 * dblk + r32) * VLP + 8 * hi;
; #pragma unroll
;                 for (int s = 0; s < 8; ++s) if (s < 4 || iblk >= 2) {
;                     const bf16x8 vf = *(const LAS bf16x8*)(vl + 16 * s);
;                     acc = __builtin_amdgcn_mfma_f32_32x32x16_bf16(vf, wf[s], acc, 0, 0, 0);
;                 }
.Lp3r_body1:
	s_add_u32 s44, s45, 2
	s_cmp_lt_u32 s44, s18
	s_cbranch_scc0 .Lp3r_tail1
	global_load_dwordx4 v[16:19], v112, s[26:27]
	global_load_dwordx4 v[20:23], v112, s[26:27] offset:16
	global_load_dwordx4 v[24:27], v233, s[26:27]
	global_load_dwordx4 v[28:31], v233, s[26:27] offset:16
	s_add_u32 s26, s26, 0x60000
	s_addc_u32 s27, s27, 0
	s_waitcnt vmcnt(11)
	v_lshlrev_b32_e32 v200, 16, v40
	v_and_b32_e32 v201, s38, v40
	v_lshlrev_b32_e32 v202, 16, v41
	v_and_b32_e32 v203, s38, v41
	v_lshlrev_b32_e32 v204, 16, v42
	v_and_b32_e32 v205, s38, v42
	v_lshlrev_b32_e32 v206, 16, v43
	v_and_b32_e32 v207, s38, v43
	s_waitcnt vmcnt(10)
	v_lshlrev_b32_e32 v208, 16, v44
	v_and_b32_e32 v209, s38, v44
	v_lshlrev_b32_e32 v210, 16, v45
	v_and_b32_e32 v211, s38, v45
	v_lshlrev_b32_e32 v212, 16, v46
	v_and_b32_e32 v213, s38, v46
	v_lshlrev_b32_e32 v214, 16, v47
	v_and_b32_e32 v215, s38, v47
	v_pk_add_f32 v[216:217], v[200:201], v[202:203]
	v_pk_add_f32 v[218:219], v[204:205], v[206:207]
	v_pk_add_f32 v[220:221], v[208:209], v[210:211]
	v_pk_add_f32 v[222:223], v[212:213], v[214:215]
	v_pk_add_f32 v[216:217], v[216:217], v[218:219]
	v_pk_add_f32 v[220:221], v[220:221], v[222:223]
	v_pk_add_f32 v[216:217], v[216:217], v[220:221]
	v_add_f32_e32 v216, v216, v217
	s_nop 1
	v_add_f32_dpp v217, v216, v216 quad_perm:[1,0,3,2] row_mask:0xf bank_mask:0xf
	s_nop 1
	v_add_f32_dpp v216, v217, v217 quad_perm:[2,3,0,1] row_mask:0xf bank_mask:0xf
	v_mul_f32_e32 v216, 0xbc800000, v216
	v_pk_add_f32 v[200:201], v[200:201], v[216:217] op_sel_hi:[1,0]
	v_pk_add_f32 v[202:203], v[202:203], v[216:217] op_sel_hi:[1,0]
	v_pk_add_f32 v[204:205], v[204:205], v[216:217] op_sel_hi:[1,0]
	v_pk_add_f32 v[206:207], v[206:207], v[216:217] op_sel_hi:[1,0]
	v_pk_add_f32 v[208:209], v[208:209], v[216:217] op_sel_hi:[1,0]
	v_pk_add_f32 v[210:211], v[210:211], v[216:217] op_sel_hi:[1,0]
	v_pk_add_f32 v[212:213], v[212:213], v[216:217] op_sel_hi:[1,0]
	v_pk_add_f32 v[214:215], v[214:215], v[216:217] op_sel_hi:[1,0]
	v_pk_mul_f32 v[218:219], v[200:201], v[200:201]
	v_pk_mul_f32 v[220:221], v[202:203], v[202:203]
	v_pk_fma_f32 v[218:219], v[204:205], v[204:205], v[218:219]
	v_pk_fma_f32 v[220:221], v[206:207], v[206:207], v[220:221]
	v_pk_fma_f32 v[218:219], v[208:209], v[208:209], v[218:219]
	v_pk_fma_f32 v[220:221], v[210:211], v[210:211], v[220:221]
	v_pk_fma_f32 v[218:219], v[212:213], v[212:213], v[218:219]
	v_pk_fma_f32 v[220:221], v[214:215], v[214:215], v[220:221]
	v_pk_add_f32 v[218:219], v[218:219], v[220:221]
	v_add_f32_e32 v218, v218, v219
	s_nop 1
	v_add_f32_dpp v219, v218, v218 quad_perm:[1,0,3,2] row_mask:0xf bank_mask:0xf
	s_nop 1
	v_add_f32_dpp v218, v219, v219 quad_perm:[2,3,0,1] row_mask:0xf bank_mask:0xf
	v_fmamk_f32 v218, v218, 0x3c800000, v111
	v_rsq_f32_e32 v218, v218
	s_nop 0
	v_pk_mul_f32 v[200:201], v[200:201], v[218:219] op_sel_hi:[1,0]
	v_pk_mul_f32 v[202:203], v[202:203], v[218:219] op_sel_hi:[1,0]
	v_pk_mul_f32 v[204:205], v[204:205], v[218:219] op_sel_hi:[1,0]
	v_pk_mul_f32 v[206:207], v[206:207], v[218:219] op_sel_hi:[1,0]
	v_pk_mul_f32 v[208:209], v[208:209], v[218:219] op_sel_hi:[1,0]
	v_pk_mul_f32 v[210:211], v[210:211], v[218:219] op_sel_hi:[1,0]
	v_pk_mul_f32 v[212:213], v[212:213], v[218:219] op_sel_hi:[1,0]
	v_pk_mul_f32 v[214:215], v[214:215], v[218:219] op_sel_hi:[1,0]
	v_pk_fma_f32 v[200:201], v[200:201], v[152:153], v[168:169]
	v_pk_fma_f32 v[202:203], v[202:203], v[154:155], v[170:171]
	v_pk_fma_f32 v[204:205], v[204:205], v[156:157], v[172:173]
	v_pk_fma_f32 v[206:207], v[206:207], v[158:159], v[174:175]
	v_pk_fma_f32 v[208:209], v[208:209], v[160:161], v[176:177]
	v_pk_fma_f32 v[210:211], v[210:211], v[162:163], v[178:179]
	v_pk_fma_f32 v[212:213], v[212:213], v[164:165], v[180:181]
	v_pk_fma_f32 v[214:215], v[214:215], v[166:167], v[182:183]
	v_cvt_pk_bf16_f32 v224, v200, v201
	v_cvt_pk_bf16_f32 v225, v202, v203
	v_cvt_pk_bf16_f32 v226, v204, v205
	v_cvt_pk_bf16_f32 v227, v206, v207
	v_cvt_pk_bf16_f32 v228, v208, v209
	v_cvt_pk_bf16_f32 v229, v210, v211
	v_cvt_pk_bf16_f32 v230, v212, v213
	v_cvt_pk_bf16_f32 v231, v214, v215
	ds_write_b16 v117, v224 offset:17536
	ds_write_b16_d16_hi v117, v224 offset:17808
	ds_write_b16 v117, v225 offset:18080
	ds_write_b16_d16_hi v117, v225 offset:18352
	ds_write_b16 v117, v226 offset:18624
	ds_write_b16_d16_hi v117, v226 offset:18896
	ds_write_b16 v117, v227 offset:19168
	ds_write_b16_d16_hi v117, v227 offset:19440
	ds_write_b16 v117, v228 offset:19712
	ds_write_b16_d16_hi v117, v228 offset:19984
	ds_write_b16 v117, v229 offset:20256
	ds_write_b16_d16_hi v117, v229 offset:20528
	ds_write_b16 v117, v230 offset:20800
	ds_write_b16_d16_hi v117, v230 offset:21072
	ds_write_b16 v117, v231 offset:21344
	ds_write_b16_d16_hi v117, v231 offset:21616
	s_waitcnt lgkmcnt(0)
	s_barrier
	ds_read_b128 v[88:91], v118 offset:17536
	ds_read_b128 v[92:95], v118 offset:17568
	ds_read_b128 v[96:99], v118 offset:17600
	ds_read_b128 v[100:103], v118 offset:17632
	s_waitcnt lgkmcnt(3)
	v_mfma_f32_32x32x16_bf16 v[0:15], v[88:91], v[120:123], 0
	s_waitcnt lgkmcnt(2)
	v_mfma_f32_32x32x16_bf16 v[0:15], v[92:95], v[124:127], v[0:15]
	s_waitcnt lgkmcnt(1)
	v_mfma_f32_32x32x16_bf16 v[0:15], v[96:99], v[128:131], v[0:15]
	s_waitcnt lgkmcnt(0)
	v_mfma_f32_32x32x16_bf16 v[0:15], v[100:103], v[132:135], v[0:15]
	s_cmp_lt_u32 s20, 0x100
	s_cbranch_scc1 .Lp3r_half1
	ds_read_b128 v[88:91], v118 offset:17664
	ds_read_b128 v[92:95], v118 offset:17696
	ds_read_b128 v[96:99], v118 offset:17728
	ds_read_b128 v[100:103], v118 offset:17760
	s_waitcnt lgkmcnt(3)
	v_mfma_f32_32x32x16_bf16 v[0:15], v[88:91], v[136:139], v[0:15]
	s_waitcnt lgkmcnt(2)
	v_mfma_f32_32x32x16_bf16 v[0:15], v[92:95], v[140:143], v[0:15]
	s_waitcnt lgkmcnt(1)
	v_mfma_f32_32x32x16_bf16 v[0:15], v[96:99], v[144:147], v[0:15]
	s_waitcnt lgkmcnt(0)
	v_mfma_f32_32x32x16_bf16 v[0:15], v[100:103], v[148:151], v[0:15]

; #define LAS __attribute__((address_space(3)))
; __device__ __forceinline__ unsigned pk2(float lo, float hi) { f32x2_t v = {lo, hi}; bf16x2_t b = __builtin_convertvector(v, bf16x2_t); return __builtin_bit_cast(unsigned, b); }
; __device__ __forceinline__ float bf_lo(unsigned u) { return __uint_as_float(u << 16); }
; __device__ __forceinline__ float bf_hi(unsigned u) { return __uint_as_float(u & 0xffff0000u); }
; __global__ void __launch_bounds__(512, 2) mega_fwd(Args a) {
;     ...
;             {
;                 float xv[16];
;                 xv[0] = bf_lo(r0.x); xv[1] = bf_hi(r0.x); xv[2] = bf_lo(r0.y); xv[3] = bf_hi(r0.y); xv[4] = bf_lo(r0.z); xv[5] = bf_hi(r0.z); xv[6] = bf_lo(r0.w); xv[7] = bf_hi(r0.w);
;                 xv[8] = bf_lo(r1.x); xv[9] = bf_hi(r1.x); xv[10] = bf_lo(r1.y); xv[11] = bf_hi(r1.y); xv[12] = bf_lo(r1.z); xv[13] = bf_hi(r1.z); xv[14] = bf_lo(r1.w); xv[15] = bf_hi(r1.w);
;                 float sm = 0.f;
; #pragma unroll
;                 for (int e = 0; e < 16; ++e) sm += xv[e];
;                 sm += __shfl_xor(sm, 1); sm += __shfl_xor(sm, 2);
;                 const float mu = sm * (1.0f / 64.0f); float q = 0.f;
; #pragma unroll
;                 for (int e = 0; e < 16; ++e) { xv[e] -= mu; q += xv[e] * xv[e]; }
;                 q += __shfl_xor(q, 1); q += __shfl_xor(q, 2);
;                 const float rstd = rsqrtf(q * (1.0f / 64.0f) + EPS);
; #pragma unroll
;                 for (int e = 0; e < 16; ++e) { const float y = xv[e] * rstd * lgv[e >> 2][e & 3] + lbv[e >> 2][e & 3]; VLT[(16 * qd + e) * VLP + jt] = (bf16_t)(pk2(y, 0.f) & 0xffffu); }
;             }
;     ...
;             __syncthreads();
;             {
;                 f32x16 acc;
; #pragma unroll
;                 for (int r = 0; r < 16; ++r) acc[r] = 0.f;
;                 const LAS bf16_t* vl = VLT + (32 * dblk + r32) * VLP + 8 * hi;
; #pragma unroll
;                 for (int s = 0; s < 8; ++s) if (s < 4 || iblk >= 2) {
;                     const bf16x8 vf = *(const LAS bf16x8*)(vl + 16 * s);
;                     acc = __builtin_amdgcn_mfma_f32_32x32x16_bf16(vf, wf[s], acc, 0, 0, 0);
;                 }
.Lp3r_body2:
	s_add_u32 s44, s45, 2
	s_cmp_lt_u32 s44, s18
	s_cbranch_scc0 .Lp3r_tail2
	global_load_dwordx4 v[40:43], v112, s[26:27]
	global_load_dwordx4 v[44:47], v112, s[26:27] offset:16
	global_load_dwordx4 v[48:51], v233, s[26:27]
	global_load_dwordx4 v[52:55], v233, s[26:27] offset:16
	s_add_u32 s26, s26, 0x60000
	s_addc_u32 s27, s27, 0
	s_waitcnt vmcnt(11)
	v_lshlrev_b32_e32 v200, 16, v56
	v_and_b32_e32 v201, s38, v56
	v_lshlrev_b32_e32 v202, 16, v57
	v_and_b32_e32 v203, s38, v57
	v_lshlrev_b32_e32 v204, 16, v58
	v_and_b32_e32 v205, s38, v58
	v_lshlrev_b32_e32 v206, 16, v59
	v_and_b32_e32 v207, s38, v59
	s_waitcnt vmcnt(10)
	v_lshlrev_b32_e32 v208, 16, v60
	v_and_b32_e32 v209, s38, v60
	v_lshlrev_b32_e32 v210, 16, v61
	v_and_b32_e32 v211, s38, v61
	v_lshlrev_b32_e32 v212, 16, v62
	v_and_b32_e32 v213, s38, v62
	v_lshlrev_b32_e32 v214, 16, v63
	v_and_b32_e32 v215, s38, v63
	v_pk_add_f32 v[216:217], v[200:201], v[202:203]
	v_pk_add_f32 v[218:219], v[204:205], v[206:207]
	v_pk_add_f32 v[220:221], v[208:209], v[210:211]
	v_pk_add_f32 v[222:223], v[212:213], v[214:215]
	v_pk_add_f32 v[216:217], v[216:217], v[218:219]
	v_pk_add_f32 v[220:221], v[220:221], v[222:223]
	v_pk_add_f32 v[216:217], v[216:217], v[220:221]
	v_add_f32_e32 v216, v216, v217
	s_nop 1
	v_add_f32_dpp v217, v216, v216 quad_perm:[1,0,3,2] row_mask:0xf bank_mask:0xf
	s_nop 1
	v_add_f32_dpp v216, v217, v217 quad_perm:[2,3,0,1] row_mask:0xf bank_mask:0xf
	v_mul_f32_e32 v216, 0xbc800000, v216
	v_pk_add_f32 v[200:201], v[200:201], v[216:217] op_sel_hi:[1,0]
	v_pk_add_f32 v[202:203], v[202:203], v[216:217] op_sel_hi:[1,0]
	v_pk_add_f32 v[204:205], v[204:205], v[216:217] op_sel_hi:[1,0]
	v_pk_add_f32 v[206:207], v[206:207], v[216:217] op_sel_hi:[1,0]
	v_pk_add_f32 v[208:209], v[208:209], v[216:217] op_sel_hi:[1,0]
	v_pk_add_f32 v[210:211], v[210:211], v[216:217] op_sel_hi:[1,0]
	v_pk_add_f32 v[212:213], v[212:213], v[216:217] op_sel_hi:[1,0]
	v_pk_add_f32 v[214:215], v[214:215], v[216:217] op_sel_hi:[1,0]
	v_pk_mul_f32 v[218:219], v[200:201], v[200:201]
	v_pk_mul_f32 v[220:221], v[202:203], v[202:203]
	v_pk_fma_f32 v[218:219], v[204:205], v[204:205], v[218:219]
	v_pk_fma_f32 v[220:221], v[206:207], v[206:207], v[220:221]
	v_pk_fma_f32 v[218:219], v[208:209], v[208:209], v[218:219]
	v_pk_fma_f32 v[220:221], v[210:211], v[210:211], v[220:221]
	v_pk_fma_f32 v[218:219], v[212:213], v[212:213], v[218:219]
	v_pk_fma_f32 v[220:221], v[214:215], v[214:215], v[220:221]
	v_pk_add_f32 v[218:219], v[218:219], v[220:221]
	v_add_f32_e32 v218, v218, v219
	s_nop 1
	v_add_f32_dpp v219, v218, v218 quad_perm:[1,0,3,2] row_mask:0xf bank_mask:0xf
	s_nop 1
	v_add_f32_dpp v218, v219, v219 quad_perm:[2,3,0,1] row_mask:0xf bank_mask:0xf
	v_fmamk_f32 v218, v218, 0x3c800000, v111
	v_rsq_f32_e32 v218, v218
	s_nop 0
	v_pk_mul_f32 v[200:201], v[200:201], v[218:219] op_sel_hi:[1,0]
	v_pk_mul_f32 v[202:203], v[202:203], v[218:219] op_sel_hi:[1,0]
	v_pk_mul_f32 v[204:205], v[204:205], v[218:219] op_sel_hi:[1,0]
	v_pk_mul_f32 v[206:207], v[206:207], v[218:219] op_sel_hi:[1,0]
	v_pk_mul_f32 v[208:209], v[208:209], v[218:219] op_sel_hi:[1,0]
	v_pk_mul_f32 v[210:211], v[210:211], v[218:219] op_sel_hi:[1,0]
	v_pk_mul_f32 v[212:213], v[212:213], v[218:219] op_sel_hi:[1,0]
	v_pk_mul_f32 v[214:215], v[214:215], v[218:219] op_sel_hi:[1,0]
	v_pk_fma_f32 v[200:201], v[200:201], v[152:153], v[168:169]
	v_pk_fma_f32 v[202:203], v[202:203], v[154:155], v[170:171]
	v_pk_fma_f32 v[204:205], v[204:205], v[156:157], v[172:173]
	v_pk_fma_f32 v[206:207], v[206:207], v[158:159], v[174:175]
	v_pk_fma_f32 v[208:209], v[208:209], v[160:161], v[176:177]
	v_pk_fma_f32 v[210:211], v[210:211], v[162:163], v[178:179]
	v_pk_fma_f32 v[212:213], v[212:213], v[164:165], v[180:181]
	v_pk_fma_f32 v[214:215], v[214:215], v[166:167], v[182:183]
	v_cvt_pk_bf16_f32 v224, v200, v201
	v_cvt_pk_bf16_f32 v225, v202, v203
	v_cvt_pk_bf16_f32 v226, v204, v205
	v_cvt_pk_bf16_f32 v227, v206, v207
	v_cvt_pk_bf16_f32 v228, v208, v209
	v_cvt_pk_bf16_f32 v229, v210, v211
	v_cvt_pk_bf16_f32 v230, v212, v213
	v_cvt_pk_bf16_f32 v231, v214, v215
	ds_write_b16 v117, v224 offset:35072
	ds_write_b16_d16_hi v117, v224 offset:35344
	ds_write_b16 v117, v225 offset:35616
	ds_write_b16_d16_hi v117, v225 offset:35888
	ds_write_b16 v117, v226 offset:36160
	ds_write_b16_d16_hi v117, v226 offset:36432
	ds_write_b16 v117, v227 offset:36704
	ds_write_b16_d16_hi v117, v227 offset:36976
	ds_write_b16 v117, v228 offset:37248
	ds_write_b16_d16_hi v117, v228 offset:37520
	ds_write_b16 v117, v229 offset:37792
	ds_write_b16_d16_hi v117, v229 offset:38064
	ds_write_b16 v117, v230 offset:38336
	ds_write_b16_d16_hi v117, v230 offset:38608
	ds_write_b16 v117, v231 offset:38880
	ds_write_b16_d16_hi v117, v231 offset:39152
	s_waitcnt lgkmcnt(0)
	s_barrier
	ds_read_b128 v[88:91], v118 offset:35072
	ds_read_b128 v[92:95], v118 offset:35104
	ds_read_b128 v[96:99], v118 offset:35136
	ds_read_b128 v[100:103], v118 offset:35168
	s_waitcnt lgkmcnt(3)
	v_mfma_f32_32x32x16_bf16 v[0:15], v[88:91], v[120:123], 0
	s_waitcnt lgkmcnt(2)
	v_mfma_f32_32x32x16_bf16 v[0:15], v[92:95], v[124:127], v[0:15]
	s_waitcnt lgkmcnt(1)
	v_mfma_f32_32x32x16_bf16 v[0:15], v[96:99], v[128:131], v[0:15]
	s_waitcnt lgkmcnt(0)
	v_mfma_f32_32x32x16_bf16 v[0:15], v[100:103], v[132:135], v[0:15]
	s_cmp_lt_u32 s20, 0x100
	s_cbranch_scc1 .Lp3r_half2
	ds_read_b128 v[88:91], v118 offset:35200
	ds_read_b128 v[92:95], v118 offset:35232
	ds_read_b128 v[96:99], v118 offset:35264
	ds_read_b128 v[100:103], v118 offset:35296
	s_waitcnt lgkmcnt(3)
	v_mfma_f32_32x32x16_bf16 v[0:15], v[88:91], v[136:139], v[0:15]
	s_waitcnt lgkmcnt(2)
	v_mfma_f32_32x32x16_bf16 v[0:15], v[92:95], v[140:143], v[0:15]
	s_waitcnt lgkmcnt(1)
	v_mfma_f32_32x32x16_bf16 v[0:15], v[96:99], v[144:147], v[0:15]
	s_waitcnt lgkmcnt(0)
	v_mfma_f32_32x32x16_bf16 v[0:15], v[100:103], v[148:151], v[0:15]

; #define LAS __attribute__((address_space(3)))
; __device__ __forceinline__ unsigned pk2(float lo, float hi) { f32x2_t v = {lo, hi}; bf16x2_t b = __builtin_convertvector(v, bf16x2_t); return __builtin_bit_cast(unsigned, b); }
; __device__ __forceinline__ float bf_lo(unsigned u) { return __uint_as_float(u << 16); }
; __device__ __forceinline__ float bf_hi(unsigned u) { return __uint_as_float(u & 0xffff0000u); }
; __global__ void __launch_bounds__(512, 2) mega_fwd(Args a) {
;     ...
;             {
;                 float xv[16];
;                 xv[0] = bf_lo(r0.x); xv[1] = bf_hi(r0.x); xv[2] = bf_lo(r0.y); xv[3] = bf_hi(r0.y); xv[4] = bf_lo(r0.z); xv[5] = bf_hi(r0.z); xv[6] = bf_lo(r0.w); xv[7] = bf_hi(r0.w);
;                 xv[8] = bf_lo(r1.x); xv[9] = bf_hi(r1.x); xv[10] = bf_lo(r1.y); xv[11] = bf_hi(r1.y); xv[12] = bf_lo(r1.z); xv[13] = bf_hi(r1.z); xv[14] = bf_lo(r1.w); xv[15] = bf_hi(r1.w);
;                 float sm = 0.f;
; #pragma unroll
;                 for (int e = 0; e < 16; ++e) sm += xv[e];
;                 sm += __shfl_xor(sm, 1); sm += __shfl_xor(sm, 2);
;                 const float mu = sm * (1.0f / 64.0f); float q = 0.f;
; #pragma unroll
;                 for (int e = 0; e < 16; ++e) { xv[e] -= mu; q += xv[e] * xv[e]; }
;                 q += __shfl_xor(q, 1); q += __shfl_xor(q, 2);
;                 const float rstd = rsqrtf(q * (1.0f / 64.0f) + EPS);
; #pragma unroll
;                 for (int e = 0; e < 16; ++e) { const float y = xv[e] * rstd * lgv[e >> 2][e & 3] + lbv[e >> 2][e & 3]; VLT[(16 * qd + e) * VLP + jt] = (bf16_t)(pk2(y, 0.f) & 0xffffu); }
;             }
;     ...
;             __syncthreads();
;             {
;                 f32x16 acc;
; #pragma unroll
;                 for (int r = 0; r < 16; ++r) acc[r] = 0.f;
;                 const LAS bf16_t* vl = VLT + (32 * dblk + r32) * VLP + 8 * hi;
; #pragma unroll
;                 for (int s = 0; s < 8; ++s) if (s < 4 || iblk >= 2) {
;                     const bf16x8 vf = *(const LAS bf16x8*)(vl + 16 * s);
;                     acc = __builtin_amdgcn_mfma_f32_32x32x16_bf16(vf, wf[s], acc, 0, 0, 0);
;                 }
.Lp3r_tail1:
	s_waitcnt vmcnt(3)
	v_lshlrev_b32_e32 v200, 16, v40
	v_and_b32_e32 v201, s38, v40
	v_lshlrev_b32_e32 v202, 16, v41
	v_and_b32_e32 v203, s38, v41
	v_lshlrev_b32_e32 v204, 16, v42
	v_and_b32_e32 v205, s38, v42
	v_lshlrev_b32_e32 v206, 16, v43
	v_and_b32_e32 v207, s38, v43
	s_waitcnt vmcnt(2)
	v_lshlrev_b32_e32 v208, 16, v44
	v_and_b32_e32 v209, s38, v44
	v_lshlrev_b32_e32 v210, 16, v45
	v_and_b32_e32 v211, s38, v45
	v_lshlrev_b32_e32 v212, 16, v46
	v_and_b32_e32 v213, s38, v46
	v_lshlrev_b32_e32 v214, 16, v47
	v_and_b32_e32 v215, s38, v47
	v_pk_add_f32 v[216:217], v[200:201], v[202:203]
	v_pk_add_f32 v[218:219], v[204:205], v[206:207]
	v_pk_add_f32 v[220:221], v[208:209], v[210:211]
	v_pk_add_f32 v[222:223], v[212:213], v[214:215]
	v_pk_add_f32 v[216:217], v[216:217], v[218:219]
	v_pk_add_f32 v[220:221], v[220:221], v[222:223]
	v_pk_add_f32 v[216:217], v[216:217], v[220:221]
	v_add_f32_e32 v216, v216, v217
	s_nop 1
	v_add_f32_dpp v217, v216, v216 quad_perm:[1,0,3,2] row_mask:0xf bank_mask:0xf
	s_nop 1
	v_add_f32_dpp v216, v217, v217 quad_perm:[2,3,0,1] row_mask:0xf bank_mask:0xf
	v_mul_f32_e32 v216, 0xbc800000, v216
	v_pk_add_f32 v[200:201], v[200:201], v[216:217] op_sel_hi:[1,0]
	v_pk_add_f32 v[202:203], v[202:203], v[216:217] op_sel_hi:[1,0]
	v_pk_add_f32 v[204:205], v[204:205], v[216:217] op_sel_hi:[1,0]
	v_pk_add_f32 v[206:207], v[206:207], v[216:217] op_sel_hi:[1,0]
	v_pk_add_f32 v[208:209], v[208:209], v[216:217] op_sel_hi:[1,0]
	v_pk_add_f32 v[210:211], v[210:211], v[216:217] op_sel_hi:[1,0]
	v_pk_add_f32 v[212:213], v[212:213], v[216:217] op_sel_hi:[1,0]
	v_pk_add_f32 v[214:215], v[214:215], v[216:217] op_sel_hi:[1,0]
	v_pk_mul_f32 v[218:219], v[200:201], v[200:201]
	v_pk_mul_f32 v[220:221], v[202:203], v[202:203]
	v_pk_fma_f32 v[218:219], v[204:205], v[204:205], v[218:219]
	v_pk_fma_f32 v[220:221], v[206:207], v[206:207], v[220:221]
	v_pk_fma_f32 v[218:219], v[208:209], v[208:209], v[218:219]
	v_pk_fma_f32 v[220:221], v[210:211], v[210:211], v[220:221]
	v_pk_fma_f32 v[218:219], v[212:213], v[212:213], v[218:219]
	v_pk_fma_f32 v[220:221], v[214:215], v[214:215], v[220:221]
	v_pk_add_f32 v[218:219], v[218:219], v[220:221]
	v_add_f32_e32 v218, v218, v219
	s_nop 1
	v_add_f32_dpp v219, v218, v218 quad_perm:[1,0,3,2] row_mask:0xf bank_mask:0xf
	s_nop 1
	v_add_f32_dpp v218, v219, v219 quad_perm:[2,3,0,1] row_mask:0xf bank_mask:0xf
	v_fmamk_f32 v218, v218, 0x3c800000, v111
	v_rsq_f32_e32 v218, v218
	s_nop 0
	v_pk_mul_f32 v[200:201], v[200:201], v[218:219] op_sel_hi:[1,0]
	v_pk_mul_f32 v[202:203], v[202:203], v[218:219] op_sel_hi:[1,0]
	v_pk_mul_f32 v[204:205], v[204:205], v[218:219] op_sel_hi:[1,0]
	v_pk_mul_f32 v[206:207], v[206:207], v[218:219] op_sel_hi:[1,0]
	v_pk_mul_f32 v[208:209], v[208:209], v[218:219] op_sel_hi:[1,0]
	v_pk_mul_f32 v[210:211], v[210:211], v[218:219] op_sel_hi:[1,0]
	v_pk_mul_f32 v[212:213], v[212:213], v[218:219] op_sel_hi:[1,0]
	v_pk_mul_f32 v[214:215], v[214:215], v[218:219] op_sel_hi:[1,0]
	v_pk_fma_f32 v[200:201], v[200:201], v[152:153], v[168:169]
	v_pk_fma_f32 v[202:203], v[202:203], v[154:155], v[170:171]
	v_pk_fma_f32 v[204:205], v[204:205], v[156:157], v[172:173]
	v_pk_fma_f32 v[206:207], v[206:207], v[158:159], v[174:175]
	v_pk_fma_f32 v[208:209], v[208:209], v[160:161], v[176:177]
	v_pk_fma_f32 v[210:211], v[210:211], v[162:163], v[178:179]
	v_pk_fma_f32 v[212:213], v[212:213], v[164:165], v[180:181]
	v_pk_fma_f32 v[214:215], v[214:215], v[166:167], v[182:183]
	v_cvt_pk_bf16_f32 v224, v200, v201
	v_cvt_pk_bf16_f32 v225, v202, v203
	v_cvt_pk_bf16_f32 v226, v204, v205
	v_cvt_pk_bf16_f32 v227, v206, v207
	v_cvt_pk_bf16_f32 v228, v208, v209
	v_cvt_pk_bf16_f32 v229, v210, v211
	v_cvt_pk_bf16_f32 v230, v212, v213
	v_cvt_pk_bf16_f32 v231, v214, v215
	ds_write_b16 v117, v224 offset:17536
	ds_write_b16_d16_hi v117, v224 offset:17808
	ds_write_b16 v117, v225 offset:18080
	ds_write_b16_d16_hi v117, v225 offset:18352
	ds_write_b16 v117, v226 offset:18624
	ds_write_b16_d16_hi v117, v226 offset:18896
	ds_write_b16 v117, v227 offset:19168
	ds_write_b16_d16_hi v117, v227 offset:19440
	ds_write_b16 v117, v228 offset:19712
	ds_write_b16_d16_hi v117, v228 offset:19984
	ds_write_b16 v117, v229 offset:20256
	ds_write_b16_d16_hi v117, v229 offset:20528
	ds_write_b16 v117, v230 offset:20800
	ds_write_b16_d16_hi v117, v230 offset:21072
	ds_write_b16 v117, v231 offset:21344
	ds_write_b16_d16_hi v117, v231 offset:21616
	s_waitcnt lgkmcnt(0)
	s_barrier
	ds_read_b128 v[88:91], v118 offset:17536
	ds_read_b128 v[92:95], v118 offset:17568
	ds_read_b128 v[96:99], v118 offset:17600
	ds_read_b128 v[100:103], v118 offset:17632
	s_waitcnt lgkmcnt(3)
	v_mfma_f32_32x32x16_bf16 v[0:15], v[88:91], v[120:123], 0
	s_waitcnt lgkmcnt(2)
	v_mfma_f32_32x32x16_bf16 v[0:15], v[92:95], v[124:127], v[0:15]
	s_waitcnt lgkmcnt(1)
	v_mfma_f32_32x32x16_bf16 v[0:15], v[96:99], v[128:131], v[0:15]
	s_waitcnt lgkmcnt(0)
	v_mfma_f32_32x32x16_bf16 v[0:15], v[100:103], v[132:135], v[0:15]
	s_cmp_lt_u32 s20, 0x100
	s_cbranch_scc1 .Lp3r_halft1
	ds_read_b128 v[88:91], v118 offset:17664
	ds_read_b128 v[92:95], v118 offset:17696
	ds_read_b128 v[96:99], v118 offset:17728
	ds_read_b128 v[100:103], v118 offset:17760
	s_waitcnt lgkmcnt(3)
	v_mfma_f32_32x32x16_bf16 v[0:15], v[88:91], v[136:139], v[0:15]
	s_waitcnt lgkmcnt(2)
	v_mfma_f32_32x32x16_bf16 v[0:15], v[92:95], v[140:143], v[0:15]
	s_waitcnt lgkmcnt(1)
	v_mfma_f32_32x32x16_bf16 v[0:15], v[96:99], v[144:147], v[0:15]
	s_waitcnt lgkmcnt(0)
	v_mfma_f32_32x32x16_bf16 v[0:15], v[100:103], v[148:151], v[0:15]

; #define LAS __attribute__((address_space(3)))
; __device__ __forceinline__ unsigned pk2(float lo, float hi) { f32x2_t v = {lo, hi}; bf16x2_t b = __builtin_convertvector(v, bf16x2_t); return __builtin_bit_cast(unsigned, b); }
; __device__ __forceinline__ float bf_lo(unsigned u) { return __uint_as_float(u << 16); }
; __device__ __forceinline__ float bf_hi(unsigned u) { return __uint_as_float(u & 0xffff0000u); }
; __global__ void __launch_bounds__(512, 2) mega_fwd(Args a) {
;     ...
;             {
;                 float xv[16];
;                 xv[0] = bf_lo(r0.x); xv[1] = bf_hi(r0.x); xv[2] = bf_lo(r0.y); xv[3] = bf_hi(r0.y); xv[4] = bf_lo(r0.z); xv[5] = bf_hi(r0.z); xv[6] = bf_lo(r0.w); xv[7] = bf_hi(r0.w);
;                 xv[8] = bf_lo(r1.x); xv[9] = bf_hi(r1.x); xv[10] = bf_lo(r1.y); xv[11] = bf_hi(r1.y); xv[12] = bf_lo(r1.z); xv[13] = bf_hi(r1.z); xv[14] = bf_lo(r1.w); xv[15] = bf_hi(r1.w);
;                 float sm = 0.f;
; #pragma unroll
;                 for (int e = 0; e < 16; ++e) sm += xv[e];
;                 sm += __shfl_xor(sm, 1); sm += __shfl_xor(sm, 2);
;                 const float mu = sm * (1.0f / 64.0f); float q = 0.f;
; #pragma unroll
;                 for (int e = 0; e < 16; ++e) { xv[e] -= mu; q += xv[e] * xv[e]; }
;                 q += __shfl_xor(q, 1); q += __shfl_xor(q, 2);
;                 const float rstd = rsqrtf(q * (1.0f / 64.0f) + EPS);
; #pragma unroll
;                 for (int e = 0; e < 16; ++e) { const float y = xv[e] * rstd * lgv[e >> 2][e & 3] + lbv[e >> 2][e & 3]; VLT[(16 * qd + e) * VLP + jt] = (bf16_t)(pk2(y, 0.f) & 0xffffu); }
;             }
;     ...
;             __syncthreads();
;             {
;                 f32x16 acc;
; #pragma unroll
;                 for (int r = 0; r < 16; ++r) acc[r] = 0.f;
;                 const LAS bf16_t* vl = VLT + (32 * dblk + r32) * VLP + 8 * hi;
; #pragma unroll
;                 for (int s = 0; s < 8; ++s) if (s < 4 || iblk >= 2) {
;                     const bf16x8 vf = *(const LAS bf16x8*)(vl + 16 * s);
;                     acc = __builtin_amdgcn_mfma_f32_32x32x16_bf16(vf, wf[s], acc, 0, 0, 0);
;                 }
.Lp3r_tail2:
	s_waitcnt vmcnt(3)
	v_lshlrev_b32_e32 v200, 16, v56
	v_and_b32_e32 v201, s38, v56
	v_lshlrev_b32_e32 v202, 16, v57
	v_and_b32_e32 v203, s38, v57
	v_lshlrev_b32_e32 v204, 16, v58
	v_and_b32_e32 v205, s38, v58
	v_lshlrev_b32_e32 v206, 16, v59
	v_and_b32_e32 v207, s38, v59
	s_waitcnt vmcnt(2)
	v_lshlrev_b32_e32 v208, 16, v60
	v_and_b32_e32 v209, s38, v60
	v_lshlrev_b32_e32 v210, 16, v61
	v_and_b32_e32 v211, s38, v61
	v_lshlrev_b32_e32 v212, 16, v62
	v_and_b32_e32 v213, s38, v62
	v_lshlrev_b32_e32 v214, 16, v63
	v_and_b32_e32 v215, s38, v63
	v_pk_add_f32 v[216:217], v[200:201], v[202:203]
	v_pk_add_f32 v[218:219], v[204:205], v[206:207]
	v_pk_add_f32 v[220:221], v[208:209], v[210:211]
	v_pk_add_f32 v[222:223], v[212:213], v[214:215]
	v_pk_add_f32 v[216:217], v[216:217], v[218:219]
	v_pk_add_f32 v[220:221], v[220:221], v[222:223]
	v_pk_add_f32 v[216:217], v[216:217], v[220:221]
	v_add_f32_e32 v216, v216, v217
	s_nop 1
	v_add_f32_dpp v217, v216, v216 quad_perm:[1,0,3,2] row_mask:0xf bank_mask:0xf
	s_nop 1
	v_add_f32_dpp v216, v217, v217 quad_perm:[2,3,0,1] row_mask:0xf bank_mask:0xf
	v_mul_f32_e32 v216, 0xbc800000, v216
	v_pk_add_f32 v[200:201], v[200:201], v[216:217] op_sel_hi:[1,0]
	v_pk_add_f32 v[202:203], v[202:203], v[216:217] op_sel_hi:[1,0]
	v_pk_add_f32 v[204:205], v[204:205], v[216:217] op_sel_hi:[1,0]
	v_pk_add_f32 v[206:207], v[206:207], v[216:217] op_sel_hi:[1,0]
	v_pk_add_f32 v[208:209], v[208:209], v[216:217] op_sel_hi:[1,0]
	v_pk_add_f32 v[210:211], v[210:211], v[216:217] op_sel_hi:[1,0]
	v_pk_add_f32 v[212:213], v[212:213], v[216:217] op_sel_hi:[1,0]
	v_pk_add_f32 v[214:215], v[214:215], v[216:217] op_sel_hi:[1,0]
	v_pk_mul_f32 v[218:219], v[200:201], v[200:201]
	v_pk_mul_f32 v[220:221], v[202:203], v[202:203]
	v_pk_fma_f32 v[218:219], v[204:205], v[204:205], v[218:219]
	v_pk_fma_f32 v[220:221], v[206:207], v[206:207], v[220:221]
	v_pk_fma_f32 v[218:219], v[208:209], v[208:209], v[218:219]
	v_pk_fma_f32 v[220:221], v[210:211], v[210:211], v[220:221]
	v_pk_fma_f32 v[218:219], v[212:213], v[212:213], v[218:219]
	v_pk_fma_f32 v[220:221], v[214:215], v[214:215], v[220:221]
	v_pk_add_f32 v[218:219], v[218:219], v[220:221]
	v_add_f32_e32 v218, v218, v219
	s_nop 1
	v_add_f32_dpp v219, v218, v218 quad_perm:[1,0,3,2] row_mask:0xf bank_mask:0xf
	s_nop 1
	v_add_f32_dpp v218, v219, v219 quad_perm:[2,3,0,1] row_mask:0xf bank_mask:0xf
	v_fmamk_f32 v218, v218, 0x3c800000, v111
	v_rsq_f32_e32 v218, v218
	s_nop 0
	v_pk_mul_f32 v[200:201], v[200:201], v[218:219] op_sel_hi:[1,0]
	v_pk_mul_f32 v[202:203], v[202:203], v[218:219] op_sel_hi:[1,0]
	v_pk_mul_f32 v[204:205], v[204:205], v[218:219] op_sel_hi:[1,0]
	v_pk_mul_f32 v[206:207], v[206:207], v[218:219] op_sel_hi:[1,0]
	v_pk_mul_f32 v[208:209], v[208:209], v[218:219] op_sel_hi:[1,0]
	v_pk_mul_f32 v[210:211], v[210:211], v[218:219] op_sel_hi:[1,0]
	v_pk_mul_f32 v[212:213], v[212:213], v[218:219] op_sel_hi:[1,0]
	v_pk_mul_f32 v[214:215], v[214:215], v[218:219] op_sel_hi:[1,0]
	v_pk_fma_f32 v[200:201], v[200:201], v[152:153], v[168:169]
	v_pk_fma_f32 v[202:203], v[202:203], v[154:155], v[170:171]
	v_pk_fma_f32 v[204:205], v[204:205], v[156:157], v[172:173]
	v_pk_fma_f32 v[206:207], v[206:207], v[158:159], v[174:175]
	v_pk_fma_f32 v[208:209], v[208:209], v[160:161], v[176:177]
	v_pk_fma_f32 v[210:211], v[210:211], v[162:163], v[178:179]
	v_pk_fma_f32 v[212:213], v[212:213], v[164:165], v[180:181]
	v_pk_fma_f32 v[214:215], v[214:215], v[166:167], v[182:183]
	v_cvt_pk_bf16_f32 v224, v200, v201
	v_cvt_pk_bf16_f32 v225, v202, v203
	v_cvt_pk_bf16_f32 v226, v204, v205
	v_cvt_pk_bf16_f32 v227, v206, v207
	v_cvt_pk_bf16_f32 v228, v208, v209
	v_cvt_pk_bf16_f32 v229, v210, v211
	v_cvt_pk_bf16_f32 v230, v212, v213
	v_cvt_pk_bf16_f32 v231, v214, v215
	ds_write_b16 v117, v224 offset:35072
	ds_write_b16_d16_hi v117, v224 offset:35344
	ds_write_b16 v117, v225 offset:35616
	ds_write_b16_d16_hi v117, v225 offset:35888
	ds_write_b16 v117, v226 offset:36160
	ds_write_b16_d16_hi v117, v226 offset:36432
	ds_write_b16 v117, v227 offset:36704
	ds_write_b16_d16_hi v117, v227 offset:36976
	ds_write_b16 v117, v228 offset:37248
	ds_write_b16_d16_hi v117, v228 offset:37520
	ds_write_b16 v117, v229 offset:37792
	ds_write_b16_d16_hi v117, v229 offset:38064
	ds_write_b16 v117, v230 offset:38336
	ds_write_b16_d16_hi v117, v230 offset:38608
	ds_write_b16 v117, v231 offset:38880
	ds_write_b16_d16_hi v117, v231 offset:39152
	s_waitcnt lgkmcnt(0)
	s_barrier
	ds_read_b128 v[88:91], v118 offset:35072
	ds_read_b128 v[92:95], v118 offset:35104
	ds_read_b128 v[96:99], v118 offset:35136
	ds_read_b128 v[100:103], v118 offset:35168
	s_waitcnt lgkmcnt(3)
	v_mfma_f32_32x32x16_bf16 v[0:15], v[88:91], v[120:123], 0
	s_waitcnt lgkmcnt(2)
	v_mfma_f32_32x32x16_bf16 v[0:15], v[92:95], v[124:127], v[0:15]
	s_waitcnt lgkmcnt(1)
	v_mfma_f32_32x32x16_bf16 v[0:15], v[96:99], v[128:131], v[0:15]
	s_waitcnt lgkmcnt(0)
	v_mfma_f32_32x32x16_bf16 v[0:15], v[100:103], v[132:135], v[0:15]
	s_cmp_lt_u32 s20, 0x100
	s_cbranch_scc1 .Lp3r_halft2
	ds_read_b128 v[88:91], v118 offset:35200
	ds_read_b128 v[92:95], v118 offset:35232
	ds_read_b128 v[96:99], v118 offset:35264
	ds_read_b128 v[100:103], v118 offset:35296
	s_waitcnt lgkmcnt(3)
	v_mfma_f32_32x32x16_bf16 v[0:15], v[88:91], v[136:139], v[0:15]
	s_waitcnt lgkmcnt(2)
	v_mfma_f32_32x32x16_bf16 v[0:15], v[92:95], v[140:143], v[0:15]
	s_waitcnt lgkmcnt(1)
	v_mfma_f32_32x32x16_bf16 v[0:15], v[96:99], v[144:147], v[0:15]
	s_waitcnt lgkmcnt(0)
	v_mfma_f32_32x32x16_bf16 v[0:15], v[100:103], v[148:151], v[0:15]
